# v32: v25 + one static s_setprio 1 for waves 0-3 (the other half) during the RG-LRU final pass and forgetting-attention phase
# speedup vs baseline: 1.0003x; 1.0003x over previous
; __device__ __forceinline__ void xcd_barrier(const XcdBarrier& b) {
;     ...
;     }
;     __syncthreads();
; __global__ void __launch_bounds__(NTHR, 2) hybrid_fwd(Args args) {
;     ...
;         GSYNC();
;         for (int it = vcu; it < 512; it += G)
.LBB0_835:
	s_or_b64 exec, exec, s[0:1]
	v_readfirstlane_b32 s0, v197
	s_nop 3
	s_lshr_b32 s0, s0, 6
	s_cmp_lt_u32 s0, 4
	s_cbranch_scc0 .Lp5_prio_done
	s_setprio 1
